# warm x rows of the first half at kernel entry (one dword per 64B per row) while the prologue runs
# baseline (speedup 1.0000x reference)
_Z14fwd_megakernel6Params:
	v_mov_b32_e32 v1, 0
	v_writelane_b32 v233, s0, 62
	v_writelane_b32 v233, s1, 63
	global_load_dword v2, v1, s[0:1] offset:246
	s_load_dwordx4 s[24:27], s[0:1], 0xe0
	s_load_dword s28, s[0:1], 0xf0
	s_load_dwordx8 s[4:11], s[0:1], 0xc0
	s_add_u32 s94, s0, 0xe8
	v_and_b32_e32 v178, 0x3ff, v0
	s_addc_u32 s95, s1, 0
	v_cmp_eq_u32_e64 s[92:93], 0, v178
	s_waitcnt lgkmcnt(0)
	v_writelane_b32 v237, s4, 0
	s_waitcnt vmcnt(0)
	v_readfirstlane_b32 s29, v2
	s_load_dwordx2 s[100:101], s[0:1], 0x0
	v_and_b32_e32 v110, 0x3ff, v0
	v_lshrrev_b32_e32 v111, 6, v110
	v_and_b32_e32 v110, 63, v110
	v_lshl_add_u32 v111, s2, 2, v111
	v_lshlrev_b32_e32 v110, 6, v110
	v_lshl_or_b32 v112, v111, 12, v110
	s_waitcnt lgkmcnt(0)
	global_load_dword v113, v112, s[100:101]
	s_add_u32 s100, s100, 0x800000
	s_addc_u32 s101, s101, 0
	global_load_dword v114, v112, s[100:101]
	s_add_u32 s100, s100, 0x800000
	s_addc_u32 s101, s101, 0
	global_load_dword v115, v112, s[100:101]
	s_add_u32 s100, s100, 0x800000
	s_addc_u32 s101, s101, 0
	global_load_dword v116, v112, s[100:101]
	s_add_u32 s100, s100, 0x800000
	s_addc_u32 s101, s101, 0
	global_load_dword v117, v112, s[100:101]
	s_add_u32 s100, s100, 0x800000
	s_addc_u32 s101, s101, 0
	global_load_dword v118, v112, s[100:101]
	s_add_u32 s100, s100, 0x800000
	s_addc_u32 s101, s101, 0
	global_load_dword v119, v112, s[100:101]
	s_add_u32 s100, s100, 0x800000
	s_addc_u32 s101, s101, 0
	global_load_dword v120, v112, s[100:101]
	v_writelane_b32 v237, s5, 1
	v_writelane_b32 v237, s6, 2
	v_writelane_b32 v237, s7, 3
	v_writelane_b32 v237, s8, 4
	v_writelane_b32 v237, s9, 5
	v_writelane_b32 v237, s10, 6
	v_writelane_b32 v237, s11, 7
	s_and_saveexec_b64 s[4:5], s[92:93]
	s_cbranch_execz .LBB0_2
	v_mov_b32_e32 v2, 0x10000
	ds_write_b32 v2, v1
	v_mov_b32_e32 v2, 0x10004
	ds_write_b32 v2, v1
